# attn_block_unit: 8 K/V band loads issued together with one wait (was 5 serialized round trips); on top of UP perm + UP counted waits
# speedup vs baseline: 1.0038x; 1.0038x over previous
; __device__ __forceinline__ void attn_block_unit(const Params& p, int bu, char* lds, int tid) {
;   const int b = bu >> 5, kv = (bu >> 4) & 1, blk = bu & 15, lane = tid & 63, wid = tid >> 6;
;   const bf16_t* Kp = (const bf16_t*)(p.ws + OFF_KP); const bf16_t* Vtp = (const bf16_t*)(p.ws + OFF_VTP);
;   char* K_l = lds; char* Vt_l = lds + ATT_VOFF;
;   u32x4 kr[4], vr[4];
; #pragma unroll
;   for (int i = 0; i < 4; ++i) {
;     const int piece = tid + i * NTHR, key = piece >> 3, c = piece & 7;
;     if (blk > 0 || key >= 128) kr[i] = *(const u32x4*)(Kp + ((size_t)b * 2048 + (size_t)(blk - 1) * 128 + key) * 128 + kv * 64 + c * 8);
;     const int d = piece >> 5, c2 = piece & 31;
;     if (blk > 0 || c2 >= 16) vr[i] = *(const u32x4*)(Vtp + ((size_t)(b * 2 + kv) * 64 + d) * 2048 + (size_t)(blk - 1) * 128 + c2 * 8);
;   }
; #pragma unroll
;   for (int i = 0; i < 4; ++i) {
;     const int piece = tid + i * NTHR, key = piece >> 3, c = piece & 7;
;     if (blk > 0 || key >= 128) *(u32x4*)(K_l + key * ATT_KSTR + c * 16) = kr[i];
;     const int d = piece >> 5, c2 = piece & 31;
;     if (blk > 0 || c2 >= 16) *(u32x4*)(Vt_l + d * ATT_VSTR + c2 * 16) = vr[i];
;   }
;   __syncthreads();
.LBB0_502:
	s_and_b32 s14, s83, 15
	s_ashr_i32 s70, s83, 5
	v_add_co_u32_e64 v8, s[10:11], s14, -1
	s_bfe_u32 s12, s83, 0x10004
	s_ashr_i32 s71, s70, 31
	v_ashrrev_i32_e32 v9, 31, v8
	s_lshl_b64 s[6:7], s[70:71], 11
	v_cndmask_b32_e64 v4, 0, 1, s[10:11]
	v_lshlrev_b64 v[2:3], 7, v[8:9]
	s_lshl_b32 s84, s12, 7
	v_lshl_add_u64 v[108:109], v[2:3], 0, s[6:7]
	v_lshl_add_u64 v[106:107], v[84:85], 0, s[84:85]
	v_cmp_ne_u32_e64 s[6:7], 1, v4
	s_andn2_b64 vcc, exec, s[10:11]
	v_mov_b32_e32 v2, v6
	v_mov_b32_e32 v3, v6
	v_mov_b32_e32 v4, v6
	v_mov_b32_e32 v5, v6
	v_or_b32_e32 v2, v108, v134
	v_mov_b32_e32 v3, v109
	v_lshlrev_b64 v[2:3], 8, v[2:3]
	v_lshl_add_u64 v[22:23], v[106:107], 0, v[2:3]
	v_lshl_add_u64 v[2:3], v[108:109], 0, v[86:87]
	v_lshlrev_b64 v[2:3], 8, v[2:3]
	v_lshl_add_u64 v[24:25], v[106:107], 0, v[2:3]
	v_lshl_add_u64 v[2:3], v[108:109], 0, v[88:89]
	v_lshlrev_b64 v[2:3], 8, v[2:3]
	v_lshl_add_u64 v[26:27], v[106:107], 0, v[2:3]
	v_lshl_add_u64 v[2:3], v[108:109], 0, v[90:91]
	v_lshlrev_b64 v[2:3], 8, v[2:3]
	v_lshl_add_u64 v[28:29], v[106:107], 0, v[2:3]
	s_lshl_b32 s13, s70, 1
	s_or_b32 s12, s13, s12
	s_ashr_i32 s13, s12, 31
	s_or_b64 s[8:9], s[10:11], s[0:1]
	s_lshl_b64 s[12:13], s[12:13], 18
	s_add_u32 s12, s3, s12
	s_addc_u32 s13, s81, s13
	v_lshlrev_b64 v[8:9], 8, v[8:9]
	v_lshl_add_u64 v[8:9], s[12:13], 0, v[8:9]
	v_mov_b32_e32 v97, v6
	v_mov_b32_e32 v99, v6
	v_mov_b32_e32 v101, v6
	v_mov_b32_e32 v103, v6
	v_mov_b32_e32 v105, v6
	v_lshl_add_u64 v[110:111], v[8:9], 0, v[96:97]
	v_lshl_add_u64 v[30:31], v[110:111], 0, v[98:99]
	v_lshl_add_u64 v[32:33], v[110:111], 0, v[100:101]
	v_lshl_add_u64 v[34:35], v[110:111], 0, v[102:103]
	v_lshl_add_u64 v[36:37], v[110:111], 0, v[104:105]
	s_and_b64 vcc, exec, s[10:11]
	s_cbranch_vccz .Lkv_ld_skip01
	global_load_dwordx4 v[38:41], v[22:23], off
	global_load_dwordx4 v[42:45], v[24:25], off
.Lkv_ld_skip01:
	global_load_dwordx4 v[46:49], v[26:27], off
	global_load_dwordx4 v[50:53], v[28:29], off
	s_and_saveexec_b64 s[12:13], s[8:9]
	s_cbranch_execz .Lkv_ld_skipv
	global_load_dwordx4 v[54:57], v[30:31], off
	global_load_dwordx4 v[58:61], v[32:33], off
	global_load_dwordx4 v[62:65], v[34:35], off
	global_load_dwordx4 v[66:69], v[36:37], off
.Lkv_ld_skipv:
	s_or_b64 exec, exec, s[12:13]
	s_waitcnt vmcnt(0)
	s_and_b64 vcc, exec, s[10:11]
	s_cbranch_vccz .Lkv_wr_skip01
	ds_write_b128 v83, v[38:41]
	ds_write_b128 v151, v[42:45]
.Lkv_wr_skip01:
	ds_write_b128 v157, v[46:49]
	ds_write_b128 v154, v[50:53]
	s_and_saveexec_b64 s[6:7], s[8:9]
	s_cbranch_execz .LBB0_524
	ds_write_b128 v150, v[54:57] offset:36864
	ds_write_b128 v152, v[58:61] offset:36864
	ds_write_b128 v153, v[62:65] offset:36864
	ds_write_b128 v155, v[66:69] offset:36864

; #define LAS __attribute__((address_space(3)))
; template <bool LDSRC>
; __device__ __forceinline__ void attn_core(const Params& p, const int lane, const char* kptr, const int kstride, const char* vptr, const int vstride,
;                                           const int kt0, const int has_prev, const int row_q, const int h_q, const int i_q) {
;     ...
;   const float sink = p.in[17][h_q];
;   const bf16_t* qp = P + (size_t)row_q * PW + 512 + h_q * 64 + q4 * 8;
;   const bf16x8 qf0 = *(const bf16x8*)qp, qf1 = *(const bf16x8*)(qp + 32);
;   u32x4 vfr[LDSRC ? 1 : 5][4];
;   if constexpr (!LDSRC) {
; #pragma unroll
;     for (int pp = 0; pp < 5; ++pp) {
;       int TA = kt0 + 2 * pp, TB = kt0 + ((2 * pp + 1 < 9) ? 2 * pp + 1 : 2 * pp);
;       if (!has_prev) { if (TA < 8) TA = 8; if (TB < 8) TB = 8; }
; #pragma unroll
;       for (int dt = 0; dt < 4; ++dt) {
;         const char* vp = vptr + (dt * 16 + pl) * vstride + q4 * 8;
;         const u32x2 va = *(const u32x2*)(vp + TA * 32), vb = *(const u32x2*)(vp + TB * 32);
;         vfr[pp][dt] = u32x4{va.x, va.y, vb.x, vb.y};
;       }
;     }
;   }
;   f32x4 sa[9];
; #pragma unroll
;   for (int kt = 0; kt < 9; ++kt) {
;     int T = kt0 + kt; if (!has_prev && T < 8) T = 8;
;     const char* kp = kptr + (T * 16 + pl) * kstride + q4 * 16;
;     bf16x8 k0, k1;
;     if constexpr (LDSRC) { k0 = *(const LAS bf16x8*)(const LAS char*)kp; k1 = *(const LAS bf16x8*)(const LAS char*)(kp + 64); }
;     else { k0 = *(const bf16x8*)kp; k1 = *(const bf16x8*)(kp + 64); }
;     f32x4 a = f32x4{0.f, 0.f, 0.f, 0.f};
;     a = __builtin_amdgcn_mfma_f32_16x16x32_bf16(k0, qf0, a, 0, 0, 0);
;     a = __builtin_amdgcn_mfma_f32_16x16x32_bf16(k1, qf1, a, 0, 0, 0);
;     sa[kt] = a;
;   }
;   const int lo = has_prev ? (i_q + 1) : ((i_q + 1) > 128 ? (i_q + 1) : 128);
;   const unsigned span = (unsigned)(i_q + 128 - lo);
;   const int dbase = q4 * 4 - lo;
;   float mx = -INFINITY;
; #pragma unroll
;   for (int kt = 0; kt < 9; ++kt) {
; #pragma unroll
;     for (int r = 0; r < 4; ++r) {
;       const int d = (kt0 + kt) * 16 + r + dbase;
;       const float v = ((unsigned)d <= span) ? sa[kt][r] : -INFINITY;
;       sa[kt][r] = v; mx = fmaxf(mx, v);
;     }
;   }
;   mx = fmaxf(mx, __shfl_xor(mx, 16)); mx = fmaxf(mx, __shfl_xor(mx, 32));
.LBB0_525:
	v_lshl_add_u64 v[4:5], v[24:25], 0, s[88:89]
	global_load_dword v2, v6, s[86:87]
	global_load_dwordx4 v[8:11], v[4:5], off offset:1024
	global_load_dwordx4 v[12:15], v[4:5], off offset:1088
	ds_read_b128 v[16:19], v64
	ds_read_b128 v[20:23], v64 offset:64
	s_mov_b32 s84, 0xff800000
	v_xor_b32_e32 v7, 16, v159
	v_add_u32_e32 v76, v148, v57
	v_add_u32_e32 v97, v147, v58
	v_add_u32_e32 v99, v147, v59
	s_waitcnt vmcnt(1) lgkmcnt(1)
	v_mfma_f32_16x16x32_bf16 v[16:19], v[16:19], v[8:11], 0
	s_waitcnt vmcnt(0) lgkmcnt(0)
	v_mfma_f32_16x16x32_bf16 v[16:19], v[20:23], v[12:15], v[16:19]
	ds_read_b128 v[20:23], v65
	ds_read_b128 v[28:31], v65 offset:64
	s_waitcnt lgkmcnt(1)
	v_mfma_f32_16x16x32_bf16 v[20:23], v[20:23], v[8:11], 0
	s_nop 3
	v_cndmask_b32_e64 v3, v16, v158, s[6:7]
	v_cndmask_b32_e64 v4, v17, v158, s[8:9]
	v_max3_f32 v5, v3, s84, v4
	s_waitcnt lgkmcnt(0)
	v_mfma_f32_16x16x32_bf16 v[20:23], v[28:31], v[12:15], v[20:23]
	ds_read_b128 v[28:31], v66
	ds_read_b128 v[32:35], v66 offset:64
	v_and_b32_e32 v16, 64, v159
	v_add_u32_e32 v16, 64, v16
	s_waitcnt lgkmcnt(1)
	v_mfma_f32_16x16x32_bf16 v[28:31], v[28:31], v[8:11], 0
	s_nop 1
	v_cndmask_b32_e64 v22, v22, v158, s[18:19]
	v_cndmask_b32_e64 v23, v23, v158, s[20:21]
	v_cmp_lt_i32_e32 vcc, v7, v16
	s_waitcnt lgkmcnt(0)
	v_mfma_f32_16x16x32_bf16 v[28:31], v[32:35], v[12:15], v[28:31]
	ds_read_b128 v[32:35], v67
	ds_read_b128 v[36:39], v67 offset:64
	v_cndmask_b32_e32 v7, v159, v7, vcc
	v_lshlrev_b32_e32 v7, 2, v7
	s_waitcnt lgkmcnt(1)
	v_mfma_f32_16x16x32_bf16 v[32:35], v[32:35], v[8:11], 0
	s_nop 1
	v_cndmask_b32_e64 v30, v30, v158, s[26:27]
	v_cndmask_b32_e64 v31, v31, v158, s[28:29]
	s_waitcnt lgkmcnt(0)
	v_mfma_f32_16x16x32_bf16 v[32:35], v[36:39], v[12:15], v[32:35]
	ds_read_b128 v[36:39], v68
	ds_read_b128 v[40:43], v68 offset:64
	s_waitcnt lgkmcnt(1)
	v_mfma_f32_16x16x32_bf16 v[36:39], v[36:39], v[8:11], 0
	s_nop 3
	v_cndmask_b32_e64 v32, v32, v158, s[30:31]
	v_cndmask_b32_e64 v33, v33, v158, s[34:35]
	v_cndmask_b32_e64 v34, v34, v158, s[36:37]
	s_waitcnt lgkmcnt(0)
	v_mfma_f32_16x16x32_bf16 v[36:39], v[40:43], v[12:15], v[36:39]
	ds_read_b128 v[40:43], v69
	ds_read_b128 v[44:47], v69 offset:64
	v_cndmask_b32_e64 v35, v35, v158, s[38:39]
	s_waitcnt lgkmcnt(1)
	v_mfma_f32_16x16x32_bf16 v[40:43], v[40:43], v[8:11], 0
	s_nop 2
	v_cndmask_b32_e64 v38, v38, v158, s[44:45]
	v_cndmask_b32_e64 v39, v39, v158, s[46:47]
	s_waitcnt lgkmcnt(0)
	v_mfma_f32_16x16x32_bf16 v[40:43], v[44:47], v[12:15], v[40:43]
	ds_read_b128 v[44:47], v70
	ds_read_b128 v[48:51], v70 offset:64
	s_waitcnt lgkmcnt(1)
	v_mfma_f32_16x16x32_bf16 v[44:47], v[44:47], v[8:11], 0
	s_nop 3
	v_cndmask_b32_e64 v40, v40, v158, s[48:49]
	v_cndmask_b32_e64 v41, v41, v158, s[50:51]
	v_cndmask_b32_e64 v42, v42, v158, s[52:53]
	s_waitcnt lgkmcnt(0)
	v_mfma_f32_16x16x32_bf16 v[44:47], v[48:51], v[12:15], v[44:47]
	ds_read_b128 v[48:51], v71
	ds_read_b128 v[52:55], v71 offset:64
	v_cndmask_b32_e64 v43, v43, v158, s[54:55]
	s_waitcnt lgkmcnt(1)
	v_mfma_f32_16x16x32_bf16 v[48:51], v[48:51], v[8:11], 0
	s_nop 2
	v_cndmask_b32_e64 v46, v46, v158, s[60:61]
	v_cndmask_b32_e64 v47, v47, v158, s[62:63]
	s_waitcnt lgkmcnt(0)
	v_mfma_f32_16x16x32_bf16 v[48:51], v[52:55], v[12:15], v[48:51]
	ds_read_b128 v[52:55], v156
	ds_read_b128 v[72:75], v156 offset:64
	s_waitcnt lgkmcnt(1)
	v_mfma_f32_16x16x32_bf16 v[8:11], v[52:55], v[8:11], 0
	v_cndmask_b32_e64 v52, v28, v158, s[22:23]
	v_cndmask_b32_e64 v53, v29, v158, s[24:25]
	v_cndmask_b32_e64 v54, v36, v158, s[40:41]
	s_waitcnt lgkmcnt(0)
	v_mfma_f32_16x16x32_bf16 v[8:11], v[72:75], v[12:15], v[8:11]
	v_cndmask_b32_e64 v12, v18, v158, s[10:11]
	v_cndmask_b32_e64 v13, v19, v158, s[12:13]
	v_max3_f32 v5, v5, v12, v13
	v_cndmask_b32_e64 v14, v20, v158, s[14:15]
	v_cndmask_b32_e64 v15, v21, v158, s[16:17]
	v_max3_f32 v5, v5, v14, v15
	v_max3_f32 v5, v5, v22, v23
	v_max3_f32 v5, v5, v52, v53
	v_max3_f32 v5, v5, v30, v31
	v_max3_f32 v5, v5, v32, v33
	v_max3_f32 v5, v5, v34, v35
	v_cndmask_b32_e64 v55, v37, v158, s[42:43]
	v_max3_f32 v5, v5, v54, v55
	v_max3_f32 v5, v5, v38, v39
	v_max3_f32 v5, v5, v40, v41
	v_max3_f32 v5, v5, v42, v43
	v_cndmask_b32_e64 v73, v44, v158, s[56:57]
	v_cndmask_b32_e64 v74, v45, v158, s[58:59]
	v_max3_f32 v5, v5, v73, v74
	v_max3_f32 v5, v5, v46, v47
	v_cndmask_b32_e64 v48, v48, v158, s[64:65]
	v_cndmask_b32_e64 v49, v49, v158, s[66:67]
	v_max3_f32 v5, v5, v48, v49
	v_cndmask_b32_e64 v50, v50, v158, s[68:69]
	v_cndmask_b32_e64 v51, v51, v158, s[70:71]
	v_max3_f32 v5, v5, v50, v51
	v_cndmask_b32_e64 v8, v8, v158, s[72:73]
	v_cndmask_b32_e64 v9, v9, v158, s[74:75]
	v_max3_f32 v5, v5, v8, v9
	v_cndmask_b32_e64 v10, v10, v158, s[76:77]
	v_cndmask_b32_e64 v11, v11, v158, s[78:79]
	v_max3_f32 v5, v5, v10, v11
	ds_bpermute_b32 v17, v7, v5
	s_waitcnt lgkmcnt(0)
	v_max_f32_e32 v17, v17, v17
	v_max_f32_e32 v5, v5, v17
	v_xor_b32_e32 v17, 32, v159
	v_cmp_lt_i32_e32 vcc, v17, v16
	s_nop 1
	v_cndmask_b32_e32 v16, v159, v17, vcc
	v_lshlrev_b32_e32 v72, 2, v16
	ds_bpermute_b32 v16, v72, v5
	s_waitcnt lgkmcnt(0)
; __device__ __forceinline__ unsigned pk2(float lo, float hi) { f32x2 v = {lo, hi}; bf16v2_t b = __builtin_convertvector(v, bf16v2_t); return __builtin_bit_cast(unsigned, b); }
; #define LAS __attribute__((address_space(3)))
; template <bool LDSRC>
; __device__ __forceinline__ void attn_core(const Params& p, const int lane, const char* kptr, const int kstride, const char* vptr, const int vstride,
;                                           const int kt0, const int has_prev, const int row_q, const int h_q, const int i_q) {
;     ...
;   const float mfin = fmaxf(mx * 0.125f, sink);
;   const float cl = 0.125f * 1.4426950408889634f, ml = mfin * 1.4426950408889634f;
;   float sum = 0.f;
; #pragma unroll
;   for (int kt = 0; kt < 9; ++kt) {
; #pragma unroll
;     for (int r = 0; r < 4; ++r) { const float e = __builtin_amdgcn_exp2f(fmaf(sa[kt][r], cl, -ml)); sa[kt][r] = e; sum += e; }
;   }
;   sum += __shfl_xor(sum, 16); sum += __shfl_xor(sum, 32);
;   const float inv = 1.f / (sum + __builtin_amdgcn_exp2f((sink - mfin) * 1.4426950408889634f));
;   f32x4 oa[4];
; #pragma unroll
;   for (int dt = 0; dt < 4; ++dt) oa[dt] = f32x4{0.f, 0.f, 0.f, 0.f};
; #pragma unroll
;   for (int pp = 0; pp < 5; ++pp) {
;     const int kA = 2 * pp, kB = (2 * pp + 1 < 9) ? 2 * pp + 1 : 2 * pp;
;     u32x4 pw;
;     pw.x = pk2(sa[kA][0] * inv, sa[kA][1] * inv); pw.y = pk2(sa[kA][2] * inv, sa[kA][3] * inv);
;     if (2 * pp + 1 < 9) { pw.z = pk2(sa[kB][0] * inv, sa[kB][1] * inv); pw.w = pk2(sa[kB][2] * inv, sa[kB][3] * inv); }
;     else { pw.z = 0u; pw.w = 0u; }
;     const bf16x8 pf = __builtin_bit_cast(bf16x8, pw);
;     if constexpr (LDSRC) {
;       int TA = kt0 + 2 * pp, TB = kt0 + ((2 * pp + 1 < 9) ? 2 * pp + 1 : 2 * pp);
;       if (!has_prev) { if (TA < 8) TA = 8; if (TB < 8) TB = 8; }
; #pragma unroll
;       for (int dt = 0; dt < 4; ++dt) {
;         const char* vp = vptr + (dt * 16 + pl) * vstride + q4 * 8;
;         const u32x2 va = *(const LAS u32x2*)(const LAS char*)(vp + TA * 32), vb = *(const LAS u32x2*)(const LAS char*)(vp + TB * 32);
;         oa[dt] = __builtin_amdgcn_mfma_f32_16x16x32_bf16(__builtin_bit_cast(bf16x8, u32x4{va.x, va.y, vb.x, vb.y}), pf, oa[dt], 0, 0, 0);
	v_max_f32_e32 v16, v16, v16
	v_max_f32_e32 v5, v5, v16
	v_mul_f32_e32 v5, 0x3e000000, v5
	v_max_f32_e32 v16, v2, v2
	v_max_f32_e32 v5, v5, v16
	v_mul_f32_e32 v75, 0xbfb8aa3b, v5
	v_fmamk_f32 v3, v3, 0x3e38aa3b, v75
	v_exp_f32_e32 v16, v3
	v_fmamk_f32 v3, v4, 0x3e38aa3b, v75
	v_exp_f32_e32 v17, v3
	v_fmamk_f32 v3, v12, 0x3e38aa3b, v75
	v_exp_f32_e32 v18, v3
	v_fmamk_f32 v3, v13, 0x3e38aa3b, v75
	v_exp_f32_e32 v19, v3
	v_fmamk_f32 v3, v14, 0x3e38aa3b, v75
	v_exp_f32_e32 v20, v3
	v_fmamk_f32 v3, v15, 0x3e38aa3b, v75
	v_exp_f32_e32 v21, v3
	v_fmamk_f32 v3, v22, 0x3e38aa3b, v75
	v_exp_f32_e32 v28, v3
	v_fmamk_f32 v3, v23, 0x3e38aa3b, v75
	v_exp_f32_e32 v29, v3
	v_fmamk_f32 v3, v52, 0x3e38aa3b, v75
	v_exp_f32_e32 v22, v3
	v_fmamk_f32 v3, v53, 0x3e38aa3b, v75
	v_exp_f32_e32 v23, v3
	v_fmamk_f32 v3, v30, 0x3e38aa3b, v75
	v_exp_f32_e32 v30, v3
	v_fmamk_f32 v3, v31, 0x3e38aa3b, v75
	v_exp_f32_e32 v31, v3
	v_fmamk_f32 v3, v32, 0x3e38aa3b, v75
	v_exp_f32_e32 v32, v3
	v_fmamk_f32 v3, v33, 0x3e38aa3b, v75
	v_exp_f32_e32 v33, v3
	v_fmamk_f32 v3, v34, 0x3e38aa3b, v75
	v_exp_f32_e32 v36, v3
	v_fmamk_f32 v3, v35, 0x3e38aa3b, v75
	v_exp_f32_e32 v37, v3
	v_fmamk_f32 v3, v54, 0x3e38aa3b, v75
	v_exp_f32_e32 v34, v3
	v_fmamk_f32 v3, v55, 0x3e38aa3b, v75
	v_exp_f32_e32 v35, v3
	v_fmamk_f32 v3, v38, 0x3e38aa3b, v75
	v_exp_f32_e32 v38, v3
	v_fmamk_f32 v3, v39, 0x3e38aa3b, v75
	v_exp_f32_e32 v39, v3
	v_fmamk_f32 v3, v40, 0x3e38aa3b, v75
	v_exp_f32_e32 v40, v3
	v_fmamk_f32 v3, v41, 0x3e38aa3b, v75
	v_exp_f32_e32 v41, v3
	v_fmamk_f32 v3, v42, 0x3e38aa3b, v75
	v_exp_f32_e32 v44, v3
	v_fmamk_f32 v3, v43, 0x3e38aa3b, v75
	v_exp_f32_e32 v45, v3
	v_fmamk_f32 v3, v73, 0x3e38aa3b, v75
	v_exp_f32_e32 v42, v3
	v_fmamk_f32 v3, v74, 0x3e38aa3b, v75
	v_exp_f32_e32 v43, v3
	v_fmamk_f32 v3, v46, 0x3e38aa3b, v75
	v_exp_f32_e32 v46, v3
	v_fmamk_f32 v3, v47, 0x3e38aa3b, v75
	v_exp_f32_e32 v47, v3
	v_fmamk_f32 v3, v48, 0x3e38aa3b, v75
	v_exp_f32_e32 v48, v3
	v_fmamk_f32 v3, v49, 0x3e38aa3b, v75
	v_exp_f32_e32 v49, v3
	v_fmamk_f32 v3, v50, 0x3e38aa3b, v75
	v_exp_f32_e32 v52, v3
	v_fmamk_f32 v3, v51, 0x3e38aa3b, v75
	v_exp_f32_e32 v53, v3
	v_fmamk_f32 v3, v8, 0x3e38aa3b, v75
	v_exp_f32_e32 v50, v3
	v_fmamk_f32 v3, v9, 0x3e38aa3b, v75
	v_sub_f32_e32 v2, v2, v5
	v_exp_f32_e32 v51, v3
	v_fmamk_f32 v3, v10, 0x3e38aa3b, v75
	v_fmac_f32_e32 v75, 0x3e38aa3b, v11
	v_mul_f32_e32 v2, 0x3fb8aa3b, v2
	v_add_u32_e32 v12, v147, v56
	v_add_u32_e32 v14, v147, v57
	v_add_u32_e32 v74, v148, v56
	v_exp_f32_e32 v54, v3
	v_exp_f32_e32 v55, v75
	v_exp_f32_e32 v73, v2
	ds_read_b64 v[2:3], v12 offset:36864
	ds_read_b64 v[4:5], v14 offset:36864
	ds_read_b64 v[8:9], v12 offset:45312
	ds_read_b64 v[10:11], v14 offset:45312
	ds_read_b64 v[12:13], v12 offset:53760
	ds_read_b64 v[14:15], v14 offset:53760
	ds_read_b64 v[74:75], v74 offset:36864
	ds_read_b64 v[76:77], v76 offset:36864
	ds_read_b64 v[106:107], v97 offset:36864
	ds_read_b64 v[108:109], v99 offset:36864
	ds_read_b64 v[160:161], v97 offset:45312
	ds_read_b64 v[162:163], v99 offset:45312
	ds_read_b64 v[164:165], v97 offset:53760
	ds_read_b64 v[166:167], v99 offset:53760
	v_add_u32_e32 v97, v148, v58
	ds_read_b64 v[168:169], v97 offset:36864
	v_add_u32_e32 v97, v148, v59
	ds_read_b64 v[170:171], v97 offset:36864
	v_add_u32_e32 v97, v147, v60
	v_add_u32_e32 v99, v147, v61
	ds_read_b64 v[172:173], v97 offset:36864
	ds_read_b64 v[174:175], v99 offset:36864
	ds_read_b64 v[176:177], v97 offset:45312
	ds_read_b64 v[178:179], v99 offset:45312
	ds_read_b64 v[188:189], v97 offset:53760
	ds_read_b64 v[190:191], v99 offset:53760
	v_add_u32_e32 v97, v148, v60
	ds_read_b64 v[192:193], v97 offset:36864
	v_add_u32_e32 v97, v148, v61
	ds_read_b64 v[194:195], v97 offset:36864
	v_add_u32_e32 v97, v147, v62
	v_add_u32_e32 v99, v147, v63
	ds_read_b64 v[196:197], v97 offset:36864
	ds_read_b64 v[198:199], v99 offset:36864
	ds_read_b64 v[200:201], v97 offset:45312
	ds_read_b64 v[202:203], v99 offset:45312
	ds_read_b64 v[204:205], v97 offset:53760
	ds_read_b64 v[206:207], v99 offset:53760
	v_add_u32_e32 v97, v148, v62
	ds_read_b64 v[208:209], v97 offset:36864
	v_add_u32_e32 v97, v148, v63
	ds_read_b64 v[210:211], v97 offset:36864
	v_add_f32_e32 v97, 0, v16
	v_add_f32_e32 v97, v17, v97
	v_add_f32_e32 v97, v18, v97
	v_add_f32_e32 v97, v19, v97
	v_add_f32_e32 v97, v20, v97
	v_add_f32_e32 v97, v21, v97
	v_add_f32_e32 v97, v28, v97
	v_add_f32_e32 v97, v29, v97
	v_add_f32_e32 v97, v22, v97
	v_add_f32_e32 v97, v23, v97
	v_add_f32_e32 v97, v30, v97
	v_add_f32_e32 v97, v31, v97
	v_add_f32_e32 v97, v32, v97
	v_add_f32_e32 v97, v33, v97
	v_add_f32_e32 v97, v36, v97
	v_add_f32_e32 v97, v37, v97
	v_add_f32_e32 v97, v34, v97
	v_add_f32_e32 v97, v35, v97
	v_add_f32_e32 v97, v38, v97
	v_add_f32_e32 v97, v39, v97
	v_add_f32_e32 v97, v40, v97
	v_add_f32_e32 v97, v41, v97
	v_add_f32_e32 v97, v44, v97
	v_add_f32_e32 v97, v45, v97
	v_add_f32_e32 v97, v42, v97
	v_add_f32_e32 v97, v43, v97
	v_add_f32_e32 v97, v46, v97
	v_add_f32_e32 v97, v47, v97
	v_add_f32_e32 v97, v48, v97
	v_add_f32_e32 v97, v49, v97
	v_add_f32_e32 v97, v52, v97
	v_add_f32_e32 v97, v53, v97
	v_add_f32_e32 v97, v50, v97
	v_add_f32_e32 v97, v51, v97
	v_add_f32_e32 v97, v54, v97
	v_add_f32_e32 v97, v55, v97
	ds_bpermute_b32 v7, v7, v97
	s_waitcnt lgkmcnt(0)
	v_add_f32_e32 v7, v97, v7
	ds_bpermute_b32 v72, v72, v7
	s_waitcnt lgkmcnt(0)
; template <bool LDSRC>
; __device__ __forceinline__ void attn_core(const Params& p, const int lane, const char* kptr, const int kstride, const char* vptr, const int vstride,
;                                           const int kt0, const int has_prev, const int row_q, const int h_q, const int i_q) {
;     ...
;   const float inv = 1.f / (sum + __builtin_amdgcn_exp2f((sink - mfin) * 1.4426950408889634f));
;   f32x4 oa[4];
; #pragma unroll
;   for (int dt = 0; dt < 4; ++dt) oa[dt] = f32x4{0.f, 0.f, 0.f, 0.f};
; #pragma unroll
;   for (int pp = 0; pp < 5; ++pp) {
;     const int kA = 2 * pp, kB = (2 * pp + 1 < 9) ? 2 * pp + 1 : 2 * pp;
;     u32x4 pw;
;     pw.x = pk2(sa[kA][0] * inv, sa[kA][1] * inv); pw.y = pk2(sa[kA][2] * inv, sa[kA][3] * inv);
;     if (2 * pp + 1 < 9) { pw.z = pk2(sa[kB][0] * inv, sa[kB][1] * inv); pw.w = pk2(sa[kB][2] * inv, sa[kB][3] * inv); }
;     else { pw.z = 0u; pw.w = 0u; }
;     const bf16x8 pf = __builtin_bit_cast(bf16x8, pw);
;     if constexpr (LDSRC) {
;       int TA = kt0 + 2 * pp, TB = kt0 + ((2 * pp + 1 < 9) ? 2 * pp + 1 : 2 * pp);
;       if (!has_prev) { if (TA < 8) TA = 8; if (TB < 8) TB = 8; }
; #pragma unroll
;       for (int dt = 0; dt < 4; ++dt) {
;         const char* vp = vptr + (dt * 16 + pl) * vstride + q4 * 8;
;         const u32x2 va = *(const LAS u32x2*)(const LAS char*)(vp + TA * 32), vb = *(const LAS u32x2*)(const LAS char*)(vp + TB * 32);
;         oa[dt] = __builtin_amdgcn_mfma_f32_16x16x32_bf16(__builtin_bit_cast(bf16x8, u32x4{va.x, va.y, vb.x, vb.y}), pf, oa[dt], 0, 0, 0);
;       }
;     } else {
; #pragma unroll
;       for (int dt = 0; dt < 4; ++dt) oa[dt] = __builtin_amdgcn_mfma_f32_16x16x32_bf16(__builtin_bit_cast(bf16x8, vfr[pp][dt]), pf, oa[dt], 0, 0, 0);
;     }
;   }
;   bf16_t* O = (bf16_t*)(ws + OFF_O);
; #pragma unroll
;   for (int dt = 0; dt < 4; ++dt) *(u32x2*)(O + (size_t)row_q * 512 + h_q * 64 + dt * 16 + q4 * 4) = pk4(oa[dt]);
; __global__ void __launch_bounds__(512) fwd_megakernel(Params p) {
;     ...
;     for (int bu = blockIdx.x; bu < 256; bu += gridDim.x) attn_block_unit(p, bu, lds, threadIdx.x);
;     bf16_t* Hs = (bf16_t*)(lds + wid * 4352);
;     constexpr int N_S1 = 8 * 32 * 16, N_SS = 32 * 32, N_AT = 256;
; #pragma unroll 1
;     for (int u = blockIdx.x * 16 + wid; u < 4096; u += ((u & 15) + NWAVE < 15) ? NWAVE : (gridDim.x * 16 - (u & 15) + wid)) {
;       asm volatile("" ::: "memory");
	v_add_f32_e32 v7, v7, v72
	v_add_f32_e32 v7, v73, v7
	v_div_scale_f32 v72, vcc, v7, v7, 1.0
	v_rcp_f32_e32 v73, v72
	s_nop 0
	v_fma_f32 v97, -v72, v73, 1.0
	v_fmac_f32_e32 v73, v97, v73
	v_div_scale_f32 v97, vcc, 1.0, v7, 1.0
	v_mul_f32_e32 v99, v97, v73
	v_fma_f32 v101, -v72, v99, v97
	v_fmac_f32_e32 v99, v101, v73
	v_fma_f32 v72, -v72, v99, v97
	v_div_fmas_f32 v72, v72, v73, v99
	v_div_fixup_f32 v72, v72, v7, 1.0
	v_pk_mul_f32 v[16:17], v[16:17], v[72:73] op_sel_hi:[1,0]
	v_pk_mul_f32 v[18:19], v[18:19], v[72:73] op_sel_hi:[1,0]
	v_cvt_pk_bf16_f32 v16, v16, v17
	v_cvt_pk_bf16_f32 v17, v18, v19
	v_pk_mul_f32 v[18:19], v[20:21], v[72:73] op_sel_hi:[1,0]
	v_pk_mul_f32 v[20:21], v[28:29], v[72:73] op_sel_hi:[1,0]
	v_cvt_pk_bf16_f32 v18, v18, v19
	v_cvt_pk_bf16_f32 v19, v20, v21
	v_pk_mul_f32 v[20:21], v[22:23], v[72:73] op_sel_hi:[1,0]
	v_pk_mul_f32 v[22:23], v[30:31], v[72:73] op_sel_hi:[1,0]
	v_mfma_f32_16x16x32_bf16 v[2:5], v[2:5], v[16:19], 0
	v_cvt_pk_bf16_f32 v20, v20, v21
	v_cvt_pk_bf16_f32 v21, v22, v23
	v_pk_mul_f32 v[22:23], v[32:33], v[72:73] op_sel_hi:[1,0]
	v_mfma_f32_16x16x32_bf16 v[8:11], v[8:11], v[16:19], 0
	v_mul_f32_e64 v28, v36, v72
	v_mul_f32_e64 v29, v37, v72
	v_cvt_pk_bf16_f32 v22, v22, v23
	v_cvt_pk_bf16_f32 v23, v28, v29
	v_mfma_f32_16x16x32_bf16 v[12:15], v[12:15], v[16:19], 0
	v_mul_f32_e64 v28, v44, v72
	v_mul_f32_e64 v29, v45, v72
	v_mov_b32_e32 v7, v6
	v_mfma_f32_16x16x32_bf16 v[16:19], v[74:77], v[16:19], 0
	v_mfma_f32_16x16x32_bf16 v[16:19], v[168:171], v[20:23], v[16:19]
	v_mfma_f32_16x16x32_bf16 v[2:5], v[106:109], v[20:23], v[2:5]
	v_mfma_f32_16x16x32_bf16 v[8:11], v[160:163], v[20:23], v[8:11]
	v_mfma_f32_16x16x32_bf16 v[12:15], v[164:167], v[20:23], v[12:15]
	v_mul_f32_e64 v20, v34, v72
	v_mul_f32_e64 v21, v35, v72
	v_pk_mul_f32 v[22:23], v[38:39], v[72:73] op_sel_hi:[1,0]
	v_cvt_pk_bf16_f32 v20, v20, v21
	v_cvt_pk_bf16_f32 v21, v22, v23
	v_pk_mul_f32 v[22:23], v[40:41], v[72:73] op_sel_hi:[1,0]
	s_nop 0
	v_cvt_pk_bf16_f32 v22, v22, v23
	v_cvt_pk_bf16_f32 v23, v28, v29
	s_nop 1
	v_mfma_f32_16x16x32_bf16 v[28:31], v[192:195], v[20:23], v[16:19]
	s_nop 2
	v_mul_f32_e64 v16, v42, v72
	v_mul_f32_e64 v17, v43, v72
	v_mfma_f32_16x16x32_bf16 v[2:5], v[172:175], v[20:23], v[2:5]
	v_cvt_pk_bf16_f32 v32, v16, v17
	v_pk_mul_f32 v[16:17], v[46:47], v[72:73] op_sel_hi:[1,0]
	s_nop 0
	v_cvt_pk_bf16_f32 v33, v16, v17
	v_pk_mul_f32 v[16:17], v[48:49], v[72:73] op_sel_hi:[1,0]
	v_mfma_f32_16x16x32_bf16 v[8:11], v[176:179], v[20:23], v[8:11]
	v_cvt_pk_bf16_f32 v34, v16, v17
	v_pk_mul_f32 v[16:17], v[52:53], v[72:73] op_sel_hi:[1,0]
	s_nop 0
	v_cvt_pk_bf16_f32 v35, v16, v17
	v_mfma_f32_16x16x32_bf16 v[12:15], v[188:191], v[20:23], v[12:15]
	s_nop 0
	v_mfma_f32_16x16x32_bf16 v[20:23], v[196:199], v[32:35], v[2:5]
	s_nop 2
	v_mul_f32_e64 v2, v50, v72
	v_mul_f32_e64 v3, v51, v72
	v_mfma_f32_16x16x32_bf16 v[16:19], v[200:203], v[32:35], v[8:11]
	v_cvt_pk_bf16_f32 v4, v2, v3
	v_pk_mul_f32 v[2:3], v[54:55], v[72:73] op_sel_hi:[1,0]
	s_nop 0
	v_cvt_pk_bf16_f32 v5, v2, v3
	v_add_u32_e32 v2, v147, v149
	v_mfma_f32_16x16x32_bf16 v[8:11], v[208:211], v[32:35], v[28:31]
	s_nop 2
	ds_read_b64 v[28:29], v2 offset:36864
	v_mfma_f32_16x16x32_bf16 v[12:15], v[204:207], v[32:35], v[12:15]
	s_waitcnt lgkmcnt(0)
	v_mov_b32_e32 v30, v28
	v_mov_b32_e32 v31, v29
	s_nop 1
	v_mfma_f32_16x16x32_bf16 v[20:23], v[28:31], v[4:7], v[20:23]
	ds_read_b64 v[28:29], v2 offset:45312
	s_waitcnt lgkmcnt(0)
	v_mov_b32_e32 v30, v28
	v_mov_b32_e32 v31, v29
	s_nop 1
	v_mfma_f32_16x16x32_bf16 v[16:19], v[28:31], v[4:7], v[16:19]
	ds_read_b64 v[28:29], v2 offset:53760
	v_add_u32_e32 v2, v148, v149
	s_waitcnt lgkmcnt(0)
	v_mov_b32_e32 v30, v28
	v_mov_b32_e32 v31, v29
	s_nop 1
	v_mfma_f32_16x16x32_bf16 v[12:15], v[28:31], v[4:7], v[12:15]
	ds_read_b64 v[28:29], v2 offset:36864
	s_waitcnt lgkmcnt(0)
	v_mov_b32_e32 v30, v28
	v_mov_b32_e32 v31, v29
	s_nop 1
	v_mfma_f32_16x16x32_bf16 v[2:5], v[28:31], v[4:7], v[8:11]
	s_nop 2
	v_lshl_add_u64 v[8:9], v[26:27], 0, s[88:89]
	s_add_u32 s88, s88, 0x80
	s_addc_u32 s89, s89, 0
	v_cvt_pk_bf16_f32 v10, v20, v21
	v_cvt_pk_bf16_f32 v11, v22, v23
	s_add_u32 s86, s86, 4
	global_store_dwordx2 v[8:9], v[10:11], off offset:-64
	v_cvt_pk_bf16_f32 v10, v16, v17
	v_cvt_pk_bf16_f32 v11, v18, v19
	s_addc_u32 s87, s87, 0
	global_store_dwordx2 v[8:9], v[10:11], off offset:-32
	v_cvt_pk_bf16_f32 v10, v12, v13
	v_cvt_pk_bf16_f32 v11, v14, v15
	v_cvt_pk_bf16_f32 v2, v2, v3
	v_cvt_pk_bf16_f32 v3, v4, v5
	s_cmpk_lg_i32 s88, 0x200
	global_store_dwordx2 v[8:9], v[10:11], off
	global_store_dwordx2 v[8:9], v[2:3], off offset:32
	s_cbranch_scc1 .LBB0_525
	s_add_i32 s83, s83, s33
	s_add_i32 s82, s82, s33
	s_cmpk_gt_i32 s83, 0xff
	s_barrier
	s_cbranch_scc0 .LBB0_502
	s_branch .LBB0_529
.LBB0_529:
	v_readlane_b32 s4, v244, 0
	v_readlane_b32 s6, v244, 2
	v_readlane_b32 s7, v244, 3
	s_add_u32 s22, s6, 0xe200000
	s_addc_u32 s23, s7, 0
	s_add_u32 s24, s6, 0xe202000
	v_readlane_b32 s0, v244, 33
	s_addc_u32 s25, s7, 0
	s_lshl_b32 s3, s0, 4
	v_or_b32_e32 v187, s3, v183
	s_movk_i32 s0, 0x1000
	v_cmp_gt_i32_e64 s[0:1], s0, v187
	v_lshl_or_b32 v224, s33, 4, v183
	v_readlane_b32 s5, v244, 1
	s_and_saveexec_b64 s[10:11], s[0:1]
	v_readlane_b32 s66, v244, 51
	v_readlane_b32 s67, v244, 52
	s_cbranch_execz .LBB0_538
	v_readlane_b32 s12, v244, 57
	v_mov_b32_e32 v3, 0
	v_lshlrev_b32_e32 v2, 3, v79
	v_readlane_b32 s13, v244, 58
	v_readlane_b32 s28, v244, 0
	v_readlane_b32 s30, v244, 2
	v_lshl_add_u64 v[4:5], s[12:13], 0, v[2:3]
	v_lshlrev_b32_e32 v2, 4, v78
	v_mbcnt_hi_u32_b32 v90, -1, v185
	v_lshlrev_b32_e32 v8, 2, v79
	v_readlane_b32 s31, v244, 3
	s_add_u32 s12, s30, 0xe224000
	v_lshlrev_b32_e32 v83, 1, v2
	v_and_b32_e32 v2, 64, v90
	v_cmp_gt_u32_e64 s[4:5], 16, v184
	v_cmp_eq_u32_e64 s[6:7], 1, v79
	v_cmp_eq_u32_e64 s[8:9], 2, v79
	s_addc_u32 s13, s31, 0
	s_mov_b64 s[14:15], 0
	v_lshlrev_b32_e32 v81, 2, v78
	s_movk_i32 s18, 0x1800
	v_mov_b64_e32 v[6:7], s[30:31]
	v_lshlrev_b32_e32 v8, 1, v8
	v_mov_b32_e32 v9, v3
	v_xor_b32_e32 v91, 16, v90
	v_add_u32_e32 v92, 64, v2
	v_xor_b32_e32 v93, 32, v90
	v_lshlrev_b32_e32 v10, 2, v184
	s_movk_i32 s19, 0xfff
	v_mov_b32_e32 v94, v187
	v_readlane_b32 s29, v244, 1
	s_branch .LBB0_532
